# grid barrier: acquire invalidate issued at arrival (members before the spin, XCD leader right after its write-back) instead of after the release flag
# speedup vs baseline: 1.0191x; 1.0072x over previous
.LBB0_1390:
	s_or_b64 exec, exec, s[10:11]
	v_cvt_f32_u32_e32 v4, v2
	s_waitcnt vmcnt(0)
	v_readfirstlane_b32 s8, v3
	v_sub_u32_e32 v3, 0, v2
	v_rcp_iflag_f32_e32 v4, v4
	v_add_u32_e32 v5, s8, v1
	v_mul_f32_e32 v4, 0x4f7ffffe, v4
	v_cvt_u32_f32_e32 v4, v4
	v_mul_lo_u32 v1, v3, v4
	v_mul_hi_u32 v1, v4, v1
	v_add_u32_e32 v1, v4, v1
	v_mul_hi_u32 v1, v5, v1
	v_mul_lo_u32 v3, v1, v2
	v_sub_u32_e32 v3, v5, v3
	v_add_u32_e32 v4, 1, v1
	v_cmp_ge_u32_e32 vcc, v3, v2
	s_nop 1
	v_cndmask_b32_e32 v1, v1, v4, vcc
	v_sub_u32_e32 v4, v3, v2
	v_cndmask_b32_e32 v3, v3, v4, vcc
	v_add_u32_e32 v4, 1, v1
	v_cmp_ge_u32_e32 vcc, v3, v2
	v_add_u32_e32 v3, 1, v5
	s_nop 0
	v_cndmask_b32_e32 v1, v1, v4, vcc
	v_mul_lo_u32 v4, v2, v1
	v_add_u32_e32 v2, v4, v2
	v_cmp_ne_u32_e32 vcc, v3, v2
	s_and_saveexec_b64 s[8:9], vcc
	s_xor_b64 s[8:9], exec, s[8:9]
	s_cbranch_execz .LBB0_1404
	s_waitcnt lgkmcnt(0)
	buffer_inv sc1
	v_mov_b32_e32 v0, 0x2000
	global_load_dword v0, v0, s[6:7] offset:1024 sc1
	s_add_u32 s14, s6, 0x2400
	s_addc_u32 s15, s7, 0
	s_waitcnt vmcnt(0)
	v_cmp_eq_u32_e32 vcc, v0, v1
	s_and_saveexec_b64 s[10:11], vcc
	s_cbranch_execz .LBB0_1403
	s_add_u32 s12, s4, 0x629c600
	s_addc_u32 s13, s5, 0
	s_mov_b32 s26, 1
	s_mov_b64 s[16:17], 0
	s_branch .LBB0_1394

.LBB0_1403:
	s_or_b64 exec, exec, s[10:11]
	s_waitcnt vmcnt(0)
	s_waitcnt vmcnt(0)
.LBB0_1404:
	s_andn2_saveexec_b64 s[8:9], s[8:9]
	s_cbranch_execz .LBB0_1424
	s_mov_b64 s[8:9], exec
	buffer_wbl2 sc1
	s_waitcnt lgkmcnt(0)
	s_waitcnt vmcnt(0)
	buffer_inv sc1
	v_mbcnt_lo_u32_b32 v1, s8, 0
	v_mbcnt_hi_u32_b32 v1, s9, v1
	v_cmp_eq_u32_e32 vcc, 0, v1
	s_and_saveexec_b64 s[10:11], vcc
	s_cbranch_execz .LBB0_1407
	s_bcnt1_i32_b64 s8, s[8:9]
	v_mov_b32_e32 v2, s8
	v_mov_b32_e32 v3, 0x629f000
	global_atomic_add v2, v3, v2, s[4:5] offset:2048 sc0

.LBB0_1421:
	s_or_b64 exec, exec, s[4:5]
	s_mov_b64 s[4:5], exec
	v_mbcnt_lo_u32_b32 v0, s4, 0
	v_mbcnt_hi_u32_b32 v0, s5, v0
	v_cmp_eq_u32_e32 vcc, 0, v0
	s_waitcnt vmcnt(0)
	s_and_saveexec_b64 s[8:9], vcc
	s_cbranch_execz .LBB0_1423
	s_bcnt1_i32_b64 s4, s[4:5]
	v_mov_b32_e32 v0, s4
	v_mov_b32_e32 v1, 0x2000
	global_atomic_add v1, v0, s[6:7] offset:1024
.LBB0_1423:
	s_or_b64 exec, exec, s[8:9]
	s_waitcnt vmcnt(0)
